# baseline (speedup 1.0000x reference)
; #define SBAR() __builtin_amdgcn_sched_barrier(0)
; #define SLOAD(i, t) do { const long rb_ = TROW(t); const char* vt_ = (const char*)Vh + rb_ * (LDK * 2); const char* kt_ = (const char*)Kh + rb_ * (LDK * 2); \
;     sr_[i].vs0 = *(const bf16x8*)(vt_ + lo0); sr_[i].vs1 = *(const bf16x8*)(vt_ + lo0 + 32 * LDK * 2); \
;     sr_[i].ks0 = *(const bf16x8*)(kt_ + lo0); sr_[i].ks1 = *(const bf16x8*)(kt_ + lo0 + 32 * LDK * 2); } while (0)
; __device__ __forceinline__ void finishSM(f32x16& p0, f32x16& p1, float alpha, float& l_reg, bf16x8& pa0, bf16x8& pa1, bf16x8& pa2, bf16x8& pa3) {
; #pragma unroll
;   for (int r = 0; r < 16; ++r) p1[r] = __builtin_amdgcn_exp2f(p1[r]);
;   float ps = 0;
; #pragma unroll
;   for (int r = 0; r < 16; ++r) ps += p0[r];
; #pragma unroll
;   for (int r = 0; r < 16; ++r) ps += p1[r];
;   { auto rr = __builtin_amdgcn_permlane32_swap(__float_as_uint(ps), __float_as_uint(ps), false, false);
;     ps = __uint_as_float(rr[0]) + __uint_as_float(rr[1]); }
;   l_reg = l_reg * alpha + ps;
;     ...
;   PK4(p0, 0, pa0); PK4(p0, 8, pa1); PK4(p1, 0, pa2); PK4(p1, 8, pa3);
;     ...
; }
; __device__ __forceinline__ void qkt(f32x16& p0, f32x16& p1, const bf16_t* Ks, const bf16x8* qr, int r32, int hi) {
;   p0 = f32x16{}; p1 = f32x16{};
; #pragma unroll
;   for (int d0 = 0; d0 < 8; ++d0) { int cb = (d0 * 16 + hi * 8) * 2;
;     bf16x8 b0 = *reinterpret_cast<const bf16x8*>((const char*)Ks + KSWZ(r32, cb));
;     bf16x8 b1 = *reinterpret_cast<const bf16x8*>((const char*)Ks + KSWZ(32 + r32, cb));
;     p0 = __builtin_amdgcn_mfma_f32_32x32x16_bf16(b0, qr[d0], p0, 0, 0, 0);
;     p1 = __builtin_amdgcn_mfma_f32_32x32x16_bf16(b1, qr[d0], p1, 0, 0, 0); }
; }
; template <bool META>
; __device__ __forceinline__ void attn_unit(const bf16_t* Q, bf16_t* Oo, const bf16_t* __restrict__ Kb, const bf16_t* __restrict__ Vb, int b, int kvh, int h, int qb, char* lds, const int tid, const float* qn, const float* RT) {
;     ...
;   for (int j = 1; j + 1 < NT; j += 2) {
;     const int bn = bc == 2 ? 0 : bc + 1, bp = bc == 0 ? 2 : bc - 1;
;     SBAR(); qkt(pB0, pB1, (bf16_t*)((char*)K_lds + bc * SHM_K), qr, r32, hi);
;     finishSM(pA0, pA1, alA, l_reg, pa0, pa1, pa2, pa3); SBAR();
;     SLOAD(SO, j + 1);
.LBB0_260:
	s_mov_b32 s6, s28
	s_sub_u32 s0, s6, 1
	s_cselect_b32 s28, 2, s0
	s_lshl_b32 s9, s6, 14
	s_add_i32 s0, s9, 0
	v_add_u32_e32 v195, s0, v182
	ds_read_b128 v[66:69], v195 offset:49152
	ds_read_b128 v[70:73], v195 offset:50176
	ds_read_b128 v[210:213], v195 offset:51200
	ds_read_b128 v[214:217], v195 offset:52224
	s_waitcnt lgkmcnt(3)
	v_mfma_f32_32x32x16_bf16 v[82:97], v[66:69], v[98:101], 0
	v_exp_f32_e32 v144, v144
	v_exp_f32_e32 v145, v145
	v_exp_f32_e32 v142, v142
	v_exp_f32_e32 v143, v143
	v_exp_f32_e32 v140, v140
	v_exp_f32_e32 v141, v141
	v_exp_f32_e32 v138, v138
	s_waitcnt lgkmcnt(2)
	v_mfma_f32_32x32x16_bf16 v[66:81], v[70:73], v[98:101], 0
	v_exp_f32_e32 v139, v139
	v_exp_f32_e32 v136, v136
	v_exp_f32_e32 v137, v137
	v_exp_f32_e32 v134, v134
	v_exp_f32_e32 v135, v135
	v_exp_f32_e32 v132, v132
	v_exp_f32_e32 v133, v133
	s_waitcnt lgkmcnt(1)
	v_mfma_f32_32x32x16_bf16 v[82:97], v[210:213], v[102:105], v[82:97]
	v_exp_f32_e32 v130, v130
	v_exp_f32_e32 v131, v131
	s_waitcnt lgkmcnt(0)
	v_mfma_f32_32x32x16_bf16 v[66:81], v[214:217], v[102:105], v[66:81]
	ds_read_b128 v[210:213], v195 offset:53248
	ds_read_b128 v[214:217], v195 offset:54272
	s_waitcnt lgkmcnt(1)
	v_mfma_f32_32x32x16_bf16 v[82:97], v[210:213], v[106:109], v[82:97]
	s_waitcnt lgkmcnt(0)
	v_mfma_f32_32x32x16_bf16 v[66:81], v[214:217], v[106:109], v[66:81]
	ds_read_b128 v[210:213], v195 offset:55296
	ds_read_b128 v[214:217], v195 offset:56320
	s_waitcnt lgkmcnt(1)
	v_mfma_f32_32x32x16_bf16 v[82:97], v[210:213], v[110:113], v[82:97]
	s_waitcnt lgkmcnt(0)
	v_mfma_f32_32x32x16_bf16 v[66:81], v[214:217], v[110:113], v[66:81]
	ds_read_b128 v[210:213], v195 offset:57344
	ds_read_b128 v[214:217], v195 offset:58368
	s_waitcnt lgkmcnt(1)
	v_mfma_f32_32x32x16_bf16 v[82:97], v[210:213], v[114:117], v[82:97]
	s_waitcnt lgkmcnt(0)
	v_mfma_f32_32x32x16_bf16 v[66:81], v[214:217], v[114:117], v[66:81]
	ds_read_b128 v[210:213], v195 offset:59392
	ds_read_b128 v[214:217], v195 offset:60416
	s_waitcnt lgkmcnt(1)
	v_mfma_f32_32x32x16_bf16 v[82:97], v[210:213], v[118:121], v[82:97]
	s_waitcnt lgkmcnt(0)
	v_mfma_f32_32x32x16_bf16 v[66:81], v[214:217], v[118:121], v[66:81]
	ds_read_b128 v[210:213], v195 offset:61440
	ds_read_b128 v[214:217], v195 offset:62464
	s_waitcnt lgkmcnt(1)
	v_mfma_f32_32x32x16_bf16 v[82:97], v[210:213], v[122:125], v[82:97]
	s_waitcnt lgkmcnt(0)
	v_mfma_f32_32x32x16_bf16 v[66:81], v[214:217], v[122:125], v[66:81]
	ds_read_b128 v[210:213], v195 offset:63488
	ds_read_b128 v[214:217], v195 offset:64512
	v_add_f32_e32 v193, v147, v146
	v_add_f32_e32 v193, v148, v193
	v_add_f32_e32 v193, v159, v193
	v_add_f32_e32 v193, v160, v193
	v_add_f32_e32 v193, v209, v193
	v_add_f32_e32 v193, v149, v193
	v_add_f32_e32 v193, v161, v193
	v_add_f32_e32 v193, v151, v193
	v_add_f32_e32 v193, v153, v193
	v_add_f32_e32 v193, v154, v193
	v_add_f32_e32 v193, v157, v193
	v_add_f32_e32 v193, v152, v193
	v_add_f32_e32 v193, v155, v193
	v_add_f32_e32 v193, v156, v193
	v_add_f32_e32 v193, v158, v193
	v_add_f32_e32 v193, v144, v193
	v_add_f32_e32 v193, v145, v193
	v_add_f32_e32 v193, v142, v193
	v_add_f32_e32 v193, v143, v193
	v_add_f32_e32 v193, v140, v193
	v_add_f32_e32 v193, v141, v193
	v_add_f32_e32 v193, v138, v193
	v_add_f32_e32 v193, v139, v193
	v_add_f32_e32 v193, v136, v193
	v_add_f32_e32 v193, v137, v193
	s_waitcnt lgkmcnt(1)
	v_mfma_f32_32x32x16_bf16 v[82:97], v[210:213], v[126:129], v[82:97]
	v_add_f32_e32 v193, v134, v193
	v_add_f32_e32 v193, v135, v193
	v_add_f32_e32 v193, v132, v193
	v_add_f32_e32 v193, v133, v193
	v_add_f32_e32 v193, v130, v193
	v_add_f32_e32 v193, v131, v193
	v_mov_b32_e32 v195, v193
	s_waitcnt lgkmcnt(0)
	v_mfma_f32_32x32x16_bf16 v[66:81], v[214:217], v[126:129], v[66:81]
	v_cvt_pk_bf16_f32 v146, v146, v147
	v_cvt_pk_bf16_f32 v147, v148, v159
	v_cvt_pk_bf16_f32 v148, v160, v209
	v_permlane32_swap_b32_e32 v193, v195
	v_cvt_pk_bf16_f32 v149, v149, v161
	v_permlane32_swap_b32_e32 v146, v148
	v_cvt_pk_bf16_f32 v210, v151, v153
	v_cvt_pk_bf16_f32 v211, v154, v157
	v_cvt_pk_bf16_f32 v212, v152, v155
	v_cvt_pk_bf16_f32 v213, v156, v158
	v_cvt_pk_bf16_f32 v152, v144, v145
	v_cvt_pk_bf16_f32 v153, v142, v143
	v_cvt_pk_bf16_f32 v154, v140, v141
	v_cvt_pk_bf16_f32 v155, v138, v139
	v_cvt_pk_bf16_f32 v156, v136, v137
	v_cvt_pk_bf16_f32 v157, v134, v135
	v_cvt_pk_bf16_f32 v158, v132, v133
	v_cvt_pk_bf16_f32 v159, v130, v131
	v_permlane32_swap_b32_e32 v147, v149
	v_permlane32_swap_b32_e32 v210, v212
	v_permlane32_swap_b32_e32 v211, v213
	v_permlane32_swap_b32_e32 v152, v154
	v_permlane32_swap_b32_e32 v153, v155
	v_permlane32_swap_b32_e32 v156, v158
	v_permlane32_swap_b32_e32 v157, v159
	s_lshl_b32 s8, s28, 14
	v_add_u32_e32 v151, s8, v178
	ds_read_b64_tr_b16 v[214:215], v151 offset:0
	ds_read_b64_tr_b16 v[216:217], v151 offset:0x800
	ds_read_b64_tr_b16 v[218:219], v151 offset:0x1000
	ds_read_b64_tr_b16 v[220:221], v151 offset:0x1800
	ds_read_b64_tr_b16 v[222:223], v151 offset:0x2000
	ds_read_b64_tr_b16 v[224:225], v151 offset:0x2800
	ds_read_b64_tr_b16 v[226:227], v151 offset:0x3000
	ds_read_b64_tr_b16 v[228:229], v151 offset:0x3800
	s_cmpk_lg_i32 s4, 0xfd
	s_cselect_b64 s[0:1], -1, 0
	s_cmpk_eq_i32 s4, 0xfd
	s_cselect_b64 s[40:41], -1, 0
	s_and_b64 s[10:11], s[40:41], exec
	s_cselect_b32 s11, s44, s91
	s_cselect_b32 s10, s31, s90
	s_lshl_b64 s[10:11], s[10:11], 9
	s_add_i32 s19, s9, 0x4000
	s_cmp_lg_u32 s6, 2
	s_cselect_b32 s19, s19, 0
	s_add_i32 s19, s19, s18
	s_add_u32 s16, s12, s10
	s_addc_u32 s17, s13, s11
	s_mov_b32 m0, s19
	s_nop 0
	global_load_lds_dwordx4 v187, s[16:17]
	s_add_i32 m0, s19, 0x380
	s_nop 0
	global_load_lds_dwordx4 v187, s[16:17] offset:128
	s_add_u32 s16, s14, s10
	s_addc_u32 s17, s15, s11
	s_add_i32 m0, s19, 0xc000
	s_nop 0
	global_load_lds_dwordx4 v188, s[16:17]
	s_add_u32 s16, s16, 0x4000
	s_addc_u32 s17, s17, 0
	s_add_i32 m0, s19, 0xc400
	s_nop 0
	global_load_lds_dwordx4 v188, s[16:17]
	s_waitcnt lgkmcnt(6)
; #define SBAR() __builtin_amdgcn_sched_barrier(0)
; template <int D0> __device__ __forceinline__ void pv_one(f32x16& od, int vb, bf16x8 pa0, bf16x8 pa1, bf16x8 pa2, bf16x8 pa3) {
;   const s16x4 l0 = tr_read<v_rd_off(D0, 0, 0)>(vb), h0 = tr_read<v_rd_off(D0, 0, 1)>(vb), l1 = tr_read<v_rd_off(D0, 1, 0)>(vb), h1 = tr_read<v_rd_off(D0, 1, 1)>(vb);
;   const s16x4 l2 = tr_read<v_rd_off(D0, 2, 0)>(vb), h2 = tr_read<v_rd_off(D0, 2, 1)>(vb), l3 = tr_read<v_rd_off(D0, 3, 0)>(vb), h3 = tr_read<v_rd_off(D0, 3, 1)>(vb);
;   asm volatile("s_waitcnt lgkmcnt(0)" ::: "memory"); SBAR();
;     ...
;   od = __builtin_amdgcn_mfma_f32_32x32x16_bf16(pa0, PK(l0, h0), od, 0, 0, 0);
;   od = __builtin_amdgcn_mfma_f32_32x32x16_bf16(pa1, PK(l1, h1), od, 0, 0, 0);
;   od = __builtin_amdgcn_mfma_f32_32x32x16_bf16(pa2, PK(l2, h2), od, 0, 0, 0);
;   od = __builtin_amdgcn_mfma_f32_32x32x16_bf16(pa3, PK(l3, h3), od, 0, 0, 0);
;     ...
; }
; __device__ __forceinline__ void pv_d0(f32x16* o, int vb, bf16x8 pa0, bf16x8 pa1, bf16x8 pa2, bf16x8 pa3) {
;   pv_one<0>(o[0], vb, pa0, pa1, pa2, pa3); pv_one<1>(o[1], vb, pa0, pa1, pa2, pa3); pv_one<2>(o[2], vb, pa0, pa1, pa2, pa3); pv_one<3>(o[3], vb, pa0, pa1, pa2, pa3);
; }
	s_nop 0
	v_mfma_f32_32x32x16_bf16 v[2:17], v[146:149], v[214:217], v[2:17]
	ds_read_b64_tr_b16 v[214:215], v151 offset:0x200
	ds_read_b64_tr_b16 v[216:217], v151 offset:0xa00
	s_waitcnt lgkmcnt(6)
	v_mfma_f32_32x32x16_bf16 v[2:17], v[210:213], v[218:221], v[2:17]
	ds_read_b64_tr_b16 v[218:219], v151 offset:0x1200
	ds_read_b64_tr_b16 v[220:221], v151 offset:0x1a00
	s_waitcnt lgkmcnt(6)
	v_mfma_f32_32x32x16_bf16 v[2:17], v[152:155], v[222:225], v[2:17]
	ds_read_b64_tr_b16 v[222:223], v151 offset:0x2200
	ds_read_b64_tr_b16 v[224:225], v151 offset:0x2a00
	s_waitcnt lgkmcnt(6)
	v_mfma_f32_32x32x16_bf16 v[2:17], v[156:159], v[226:229], v[2:17]
	ds_read_b64_tr_b16 v[226:227], v151 offset:0x3200
	ds_read_b64_tr_b16 v[228:229], v151 offset:0x3a00
	s_waitcnt lgkmcnt(6)
	v_mfma_f32_32x32x16_bf16 v[50:65], v[146:149], v[214:217], v[50:65]
	ds_read_b64_tr_b16 v[214:215], v151 offset:0x400
	ds_read_b64_tr_b16 v[216:217], v151 offset:0xc00
	s_waitcnt lgkmcnt(6)
	v_mfma_f32_32x32x16_bf16 v[50:65], v[210:213], v[218:221], v[50:65]
	ds_read_b64_tr_b16 v[218:219], v151 offset:0x1400
	ds_read_b64_tr_b16 v[220:221], v151 offset:0x1c00
	s_waitcnt lgkmcnt(6)
	v_mfma_f32_32x32x16_bf16 v[50:65], v[152:155], v[222:225], v[50:65]
	ds_read_b64_tr_b16 v[222:223], v151 offset:0x2400
	ds_read_b64_tr_b16 v[224:225], v151 offset:0x2c00
	s_waitcnt lgkmcnt(6)
	v_mfma_f32_32x32x16_bf16 v[50:65], v[156:159], v[226:229], v[50:65]
	ds_read_b64_tr_b16 v[226:227], v151 offset:0x3400
	ds_read_b64_tr_b16 v[228:229], v151 offset:0x3c00
	s_waitcnt lgkmcnt(6)
	v_mfma_f32_32x32x16_bf16 v[34:49], v[146:149], v[214:217], v[34:49]
	ds_read_b64_tr_b16 v[214:215], v151 offset:0x600
	ds_read_b64_tr_b16 v[216:217], v151 offset:0xe00
	s_waitcnt lgkmcnt(6)
	v_mfma_f32_32x32x16_bf16 v[34:49], v[210:213], v[218:221], v[34:49]
	ds_read_b64_tr_b16 v[218:219], v151 offset:0x1600
	ds_read_b64_tr_b16 v[220:221], v151 offset:0x1e00
	s_waitcnt lgkmcnt(6)
	v_mfma_f32_32x32x16_bf16 v[34:49], v[152:155], v[222:225], v[34:49]
	ds_read_b64_tr_b16 v[222:223], v151 offset:0x2600
	ds_read_b64_tr_b16 v[224:225], v151 offset:0x2e00
	s_waitcnt lgkmcnt(6)
	v_mfma_f32_32x32x16_bf16 v[34:49], v[156:159], v[226:229], v[34:49]
	ds_read_b64_tr_b16 v[226:227], v151 offset:0x3600
	ds_read_b64_tr_b16 v[228:229], v151 offset:0x3e00
	s_waitcnt lgkmcnt(6)
	v_mfma_f32_32x32x16_bf16 v[18:33], v[146:149], v[214:217], v[18:33]
	v_max_f32_e32 v146, v82, v83
	v_max3_f32 v146, v146, v84, v85
	v_max3_f32 v146, v146, v86, v87
	v_max3_f32 v146, v146, v88, v89
	v_max3_f32 v146, v146, v90, v91
	v_max3_f32 v146, v146, v92, v93
	v_max3_f32 v146, v146, v94, v95
	v_max3_f32 v146, v146, v96, v97
	v_max3_f32 v146, v146, v66, v67
	s_waitcnt lgkmcnt(4)
	v_mfma_f32_32x32x16_bf16 v[18:33], v[210:213], v[218:221], v[18:33]
	v_max3_f32 v146, v146, v68, v69
	v_max3_f32 v146, v146, v70, v71
	v_max3_f32 v146, v146, v72, v73
	v_max3_f32 v146, v146, v74, v75
	v_max3_f32 v146, v146, v76, v77
	v_max3_f32 v146, v146, v78, v79
	v_max3_f32 v146, v146, v80, v81
	v_mov_b32_e32 v147, v146
	s_waitcnt lgkmcnt(2)
	v_mfma_f32_32x32x16_bf16 v[18:33], v[152:155], v[222:225], v[18:33]
	s_nop 0
	v_permlane32_swap_b32_e32 v146, v147
	v_max_f32_e32 v146, v146, v147
	v_sub_f32_e32 v147, v146, v150
	v_cmp_ge_f32_e32 vcc, s25, v147
	v_max_f32_e32 v146, v150, v146
	v_sub_f32_e32 v147, v150, v146
	s_cmp_eq_u64 vcc, exec
	v_mul_f32_e32 v147, 0x3e0293ee, v147
	s_waitcnt lgkmcnt(0)
	v_mfma_f32_32x32x16_bf16 v[18:33], v[156:159], v[226:229], v[18:33]
	s_cselect_b64 s[42:43], -1, 0
	v_exp_f32_e32 v147, v147
	s_add_i32 s7, s9, 0x4000
	s_cmp_lg_u32 s6, 2
	s_cselect_b32 s6, s7, 0
	s_add_i32 s10, s6, 0
	v_cndmask_b32_e64 v196, v147, 1.0, s[42:43]
	v_cmp_gt_f32_e32 vcc, 1.0, v196
	s_cbranch_vccz .LBB0_264
	s_and_saveexec_b64 s[6:7], s[38:39]
	ds_write_b32 v190, v196 offset:128
	s_or_b64 exec, exec, s[6:7]
	s_waitcnt lgkmcnt(0)
	v_add_u32_e32 v147, v173, v181
	ds_read_b128 v[152:155], v147 offset:224
	ds_read_b128 v[156:159], v147 offset:192
	ds_read_b128 v[210:213], v147 offset:160
	ds_read_b128 v[214:217], v147 offset:128
	s_waitcnt lgkmcnt(3)
	v_pk_mul_f32 v[14:15], v[14:15], v[152:153]
	s_waitcnt lgkmcnt(2)
	v_pk_mul_f32 v[10:11], v[10:11], v[156:157]
	s_waitcnt lgkmcnt(1)
	v_pk_mul_f32 v[6:7], v[6:7], v[210:211]
	v_pk_mul_f32 v[16:17], v[16:17], v[154:155]
	v_pk_mul_f32 v[12:13], v[12:13], v[158:159]
	v_pk_mul_f32 v[8:9], v[8:9], v[212:213]
	s_waitcnt lgkmcnt(0)
	v_pk_mul_f32 v[4:5], v[4:5], v[216:217]
	v_pk_mul_f32 v[2:3], v[2:3], v[214:215]
	v_pk_mul_f32 v[62:63], v[62:63], v[152:153]
	v_pk_mul_f32 v[58:59], v[58:59], v[156:157]
	v_pk_mul_f32 v[54:55], v[54:55], v[210:211]
	v_pk_mul_f32 v[64:65], v[64:65], v[154:155]
	v_pk_mul_f32 v[60:61], v[60:61], v[158:159]
	v_pk_mul_f32 v[56:57], v[56:57], v[212:213]
	v_pk_mul_f32 v[52:53], v[52:53], v[216:217]
	v_pk_mul_f32 v[50:51], v[50:51], v[214:215]
	v_pk_mul_f32 v[46:47], v[46:47], v[152:153]
	v_pk_mul_f32 v[42:43], v[42:43], v[156:157]
	v_pk_mul_f32 v[38:39], v[38:39], v[210:211]
	v_pk_mul_f32 v[48:49], v[48:49], v[154:155]
	v_pk_mul_f32 v[44:45], v[44:45], v[158:159]
	v_pk_mul_f32 v[40:41], v[40:41], v[212:213]
	v_pk_mul_f32 v[36:37], v[36:37], v[216:217]
	v_pk_mul_f32 v[34:35], v[34:35], v[214:215]
	v_pk_mul_f32 v[30:31], v[30:31], v[152:153]
	v_pk_mul_f32 v[26:27], v[26:27], v[156:157]
	v_pk_mul_f32 v[22:23], v[22:23], v[210:211]
	v_pk_mul_f32 v[32:33], v[32:33], v[154:155]
	v_pk_mul_f32 v[28:29], v[28:29], v[158:159]
	v_pk_mul_f32 v[24:25], v[24:25], v[212:213]
	v_pk_mul_f32 v[20:21], v[20:21], v[216:217]
	v_pk_mul_f32 v[18:19], v[18:19], v[214:215]

; #define SWRITE(bb, i) do { *(bf16x8*)((char*)V_lds + (bb) * SHM_V + vst0) = sr_[i].vs0;          \
;     *(bf16x8*)((char*)V_lds + (bb) * SHM_V + vst1) = sr_[i].vs1; int kc = sc * 2;               \
;     *(bf16x8*)((char*)K_lds + (bb) * SHM_K + KSWZ(sr, kc)) = sr_[i].ks0;                       \
;     *(bf16x8*)((char*)K_lds + (bb) * SHM_K + KSWZ(32 + sr, kc)) = sr_[i].ks1; } while (0)
; #define SWAIT() asm volatile("s_waitcnt vmcnt(0)" ::: "memory")
; #define RESC(a) do { if (__any((a) < 1.f)) { if (hi == 0) al_l[r32] = (a); asm volatile("s_waitcnt lgkmcnt(0)" ::: "memory"); \
;     _Pragma("unroll") for (int d = 0; d < 4; ++d) _Pragma("unroll") for (int r = 0; r < 16; ++r) o[d][r] *= al_l[crow(r, hi)]; } } while (0)
; __device__ __forceinline__ void partialSM(f32x16& p0, f32x16& p1, float& m_reg, float& mn, float& alpha) {
;     ...
;   if (__builtin_expect(__all(pmax - m_reg <= ATHR / ASCALE), 1)) { mn = m_reg; alpha = 1.f; }
;   else { mn = fmaxf(m_reg, pmax); alpha = __builtin_amdgcn_exp2f((m_reg - mn) * C); m_reg = mn; }
;   float mnC = -mn * C;
; #pragma unroll
;   for (int r = 0; r < 16; ++r) p0[r] = fmaf(p0[r], C, mnC);
; #pragma unroll
;   for (int r = 0; r < 16; ++r) p1[r] = fmaf(p1[r], C, mnC);
; #pragma unroll
;   for (int r = 0; r < 16; ++r) p0[r] = __builtin_amdgcn_exp2f(p0[r]);
; template <bool META>
; __device__ __forceinline__ void attn_unit(const bf16_t* Q, bf16_t* Oo, const bf16_t* __restrict__ Kb, const bf16_t* __restrict__ Vb, int b, int kvh, int h, int qb, char* lds, const int tid, const float* qn, const float* RT) {
;     ...
;     pv_d0(o, vb0 + bc * (int)SHM_V, pa0, pa1, pa2, pa3); partialSM(pA0, pA1, m_reg, mnA, alA);
;     SWAIT(); SWRITE(bp, SO);
;     RESC(alA); __syncthreads();
;     bc = bp;
;   }
.LBB0_270:
	v_cndmask_b32_e64 v150, v231, v209, s[40:41]
	v_mul_f32_e32 v232, 0xbe0293ee, v150
	v_fmamk_f32 v66, v66, 0x3e0293ee, v232
	v_fmamk_f32 v67, v67, 0x3e0293ee, v232
	v_fmamk_f32 v68, v68, 0x3e0293ee, v232
	v_fmamk_f32 v69, v69, 0x3e0293ee, v232
	v_fmamk_f32 v70, v70, 0x3e0293ee, v232
	v_fmamk_f32 v71, v71, 0x3e0293ee, v232
	v_fmamk_f32 v72, v72, 0x3e0293ee, v232
	v_fmamk_f32 v73, v73, 0x3e0293ee, v232
	v_fmamk_f32 v231, v74, 0x3e0293ee, v232
	v_fmamk_f32 v233, v75, 0x3e0293ee, v232
	v_fmamk_f32 v234, v76, 0x3e0293ee, v232
	v_fmamk_f32 v235, v77, 0x3e0293ee, v232
	v_fmamk_f32 v236, v78, 0x3e0293ee, v232
	v_fmamk_f32 v237, v79, 0x3e0293ee, v232
	v_fmamk_f32 v156, v80, 0x3e0293ee, v232
	v_fmamk_f32 v158, v81, 0x3e0293ee, v232
	v_exp_f32_e32 v146, v66
	v_exp_f32_e32 v147, v67
	v_exp_f32_e32 v148, v68
	v_exp_f32_e32 v159, v69
	v_exp_f32_e32 v160, v70
	v_exp_f32_e32 v209, v71
	v_exp_f32_e32 v149, v72
	v_exp_f32_e32 v161, v73
	v_exp_f32_e32 v151, v231
	v_exp_f32_e32 v153, v233
	v_exp_f32_e32 v154, v234
	v_exp_f32_e32 v157, v235
	v_exp_f32_e32 v152, v236
	v_exp_f32_e32 v155, v237
	v_exp_f32_e32 v156, v156
	v_exp_f32_e32 v158, v158
	v_add_f32_e32 v66, v193, v195
	s_add_u32 s90, s90, 0x80
	v_fmac_f32_e32 v66, v192, v0
	v_add_f32_e32 v0, v210, v211
	s_addc_u32 s91, s91, 0
	v_pk_fma_f32 v[144:145], v[82:83], s[36:37], v[232:233] op_sel_hi:[1,0,0]
	v_pk_fma_f32 v[142:143], v[84:85], s[36:37], v[232:233] op_sel_hi:[1,0,0]
	v_pk_fma_f32 v[140:141], v[86:87], s[36:37], v[232:233] op_sel_hi:[1,0,0]
	v_pk_fma_f32 v[138:139], v[88:89], s[36:37], v[232:233] op_sel_hi:[1,0,0]
	v_pk_fma_f32 v[136:137], v[90:91], s[36:37], v[232:233] op_sel_hi:[1,0,0]
	v_pk_fma_f32 v[134:135], v[92:93], s[36:37], v[232:233] op_sel_hi:[1,0,0]
	v_pk_fma_f32 v[132:133], v[94:95], s[36:37], v[232:233] op_sel_hi:[1,0,0]
	v_pk_fma_f32 v[130:131], v[96:97], s[36:37], v[232:233] op_sel_hi:[1,0,0]
	v_fmac_f32_e32 v0, v66, v196
	s_cmpk_gt_u32 s4, 0xfd
	s_waitcnt vmcnt(0)
	s_waitcnt lgkmcnt(0)
	s_barrier
	s_cbranch_scc1 .LBB0_272
	v_mov_b32_e32 v192, v230
	s_branch .LBB0_260
